# P6 carry-in Horner: same recurrence and order, the state loads of 8 steps (32 loads) kept in flight continuously instead of 16-step batches each waiting out the load latency
# speedup vs baseline: 1.0197x; 1.0069x over previous
;     __device__ __forceinline__ const float* in(int i) const { return karg_in(i); }
; template <bool PASS2>
; __device__ __forceinline__ void s5_tile(const Ctx& C, int T, int sb_lo, int sb_hi, LAS unsigned char* lds, int wave, int lane) {
;     ...
;     const float* LAM = C.LAM();
;     const bf16* Zb = C.Z() + (size_t)1024 + 64 * wave;
;     float sr[4], si[4], lr[4], li[4], dsk[4];
; #pragma unroll
;     for (int gi = 0; gi < 4; ++gi) { const int g = wave * 4 + gi; sr[gi] = 0.f; si[gi] = 0.f; lr[gi] = LAM[0 * 2048 + g * 64 + lane]; li[gi] = LAM[1 * 2048 + g * 64 + lane];
;         dsk[gi] = PASS2 ? C.in(21)[16 * g + fr] : 0.f; }
;     if (PASS2 && !sample) {
;         const int k = T & 127, tb = T - k;
;         float l8r[4], l8i[4];
; #pragma unroll
;         for (int gi = 0; gi < 4; ++gi) { l8r[gi] = LAM[2 * 2048 + (wave * 4 + gi) * 64 + lane]; l8i[gi] = LAM[3 * 2048 + (wave * 4 + gi) * 64 + lane]; }
;         const v2f* Ep = (const v2f*)C.E() + ((size_t)tb * NG + wave * 4) * NP + lane;
;         const int nb = (k + 15) >> 4, j0 = k - 16 * nb;
;         for (int jb = 0; jb < nb; ++jb) {
; #pragma unroll
;             for (int u = 0; u < 16; ++u) {
;                 const int j = j0 + 16 * jb + u; const bool ok = j >= 0; const int jc = ok ? j : 0;
; #pragma unroll
;                 for (int gi = 0; gi < 4; ++gi) { v2f e = Ep[(size_t)jc * NG * NP + gi * NP]; if (!ok) e = (v2f){0.f, 0.f};
.Lmy_p6_tile_entry:
	s_mov_b64 s[0:1], s[80:81]
	s_load_dwordx2 s[10:11], s[0:1], 0x110
	v_readfirstlane_b32 s3, v160
	s_ashr_i32 s67, s3, 6
	s_mov_b64 s[0:1], s[80:81]
	s_mov_b64 s[12:13], s[80:81]
	s_waitcnt lgkmcnt(0)
	s_add_u32 s10, s10, 0x2a40000
	s_addc_u32 s11, s11, 0
	s_lshl_b32 s14, s67, 8
	v_or_b32_e32 v0, s14, v98
	v_ashrrev_i32_e32 v1, 31, v0
	v_add_u32_e32 v2, s14, v103
	v_lshl_add_u64 v[0:1], v[0:1], 2, s[10:11]
	v_ashrrev_i32_e32 v3, 31, v2
	v_lshl_add_u64 v[2:3], v[2:3], 2, s[10:11]
	global_load_dword v173, v[0:1], off
	global_load_dword v174, v[2:3], off
	s_load_dwordx2 s[12:13], s[12:13], 0xa8
	s_and_b32 s72, s3, 0xffffffc0
	s_lshl_b32 s62, s67, 2
	v_or_b32_e32 v6, s72, v99
	v_ashrrev_i32_e32 v7, 31, v6
	s_or_b32 s64, s62, 1
	s_waitcnt lgkmcnt(0)
	v_lshl_add_u64 v[0:1], v[6:7], 2, s[12:13]
	s_lshl_b32 s3, s64, 6
	global_load_dword v175, v[0:1], off
	v_or_b32_e32 v0, s3, v98
	v_ashrrev_i32_e32 v1, 31, v0
	v_add_u32_e32 v2, s3, v103
	v_lshl_add_u64 v[0:1], v[0:1], 2, s[10:11]
	v_ashrrev_i32_e32 v3, 31, v2
	s_mov_b64 s[12:13], s[80:81]
	v_lshl_add_u64 v[2:3], v[2:3], 2, s[10:11]
	global_load_dword v176, v[0:1], off
	global_load_dword v177, v[2:3], off
	s_load_dwordx2 s[12:13], s[12:13], 0xa8
	v_lshl_or_b32 v4, s64, 4, v99
	v_ashrrev_i32_e32 v5, 31, v4
	s_or_b32 s66, s62, 2
	s_lshl_b32 s3, s66, 6
	s_waitcnt lgkmcnt(0)
	v_lshl_add_u64 v[0:1], v[4:5], 2, s[12:13]
	global_load_dword v178, v[0:1], off
	v_or_b32_e32 v0, s3, v98
	v_ashrrev_i32_e32 v1, 31, v0
	v_add_u32_e32 v2, s3, v103
	v_lshl_add_u64 v[0:1], v[0:1], 2, s[10:11]
	v_ashrrev_i32_e32 v3, 31, v2
	s_mov_b64 s[12:13], s[80:81]
	v_lshl_add_u64 v[2:3], v[2:3], 2, s[10:11]
	global_load_dword v179, v[0:1], off
	global_load_dword v180, v[2:3], off
	s_load_dwordx2 s[12:13], s[12:13], 0xa8
	v_lshl_or_b32 v2, s66, 4, v99
	v_ashrrev_i32_e32 v3, 31, v2
	s_or_b32 s68, s62, 3
	s_lshl_b32 s3, s68, 6
	s_waitcnt lgkmcnt(0)
	v_lshl_add_u64 v[0:1], v[2:3], 2, s[12:13]
	global_load_dword v181, v[0:1], off
	v_or_b32_e32 v0, s3, v98
	v_ashrrev_i32_e32 v1, 31, v0
	v_add_u32_e32 v8, s3, v103
	v_lshl_add_u64 v[0:1], v[0:1], 2, s[10:11]
	v_ashrrev_i32_e32 v9, 31, v8
	s_mov_b64 s[12:13], s[80:81]
	v_lshl_add_u64 v[8:9], v[8:9], 2, s[10:11]
	global_load_dword v189, v[0:1], off
	global_load_dword v190, v[8:9], off
	s_load_dwordx2 s[12:13], s[12:13], 0xa8
	v_lshl_or_b32 v0, s68, 4, v99
	v_ashrrev_i32_e32 v1, 31, v0
	s_or_b32 s3, s14, 64
	v_add_u32_e32 v12, s3, v105
	s_waitcnt lgkmcnt(0)
	v_lshl_add_u64 v[8:9], v[0:1], 2, s[12:13]
	v_add_u32_e32 v14, s3, v163
	s_or_b32 s3, s14, 0x80
	global_load_dword v191, v[8:9], off
	v_add_u32_e32 v8, s14, v105
	v_add_u32_e32 v10, s14, v163
	v_add_u32_e32 v16, s3, v105
	v_add_u32_e32 v18, s3, v163
	s_or_b32 s3, s14, 0xc0
	v_ashrrev_i32_e32 v9, 31, v8
	v_ashrrev_i32_e32 v11, 31, v10
	v_ashrrev_i32_e32 v13, 31, v12
	v_ashrrev_i32_e32 v15, 31, v14
	v_add_u32_e32 v20, s3, v105
	v_add_u32_e32 v22, s3, v163
	v_lshl_add_u64 v[8:9], v[8:9], 2, s[10:11]
	v_lshl_add_u64 v[10:11], v[10:11], 2, s[10:11]
	v_lshl_add_u64 v[12:13], v[12:13], 2, s[10:11]
	v_lshl_add_u64 v[14:15], v[14:15], 2, s[10:11]
	v_ashrrev_i32_e32 v17, 31, v16
	v_ashrrev_i32_e32 v19, 31, v18
	v_ashrrev_i32_e32 v21, 31, v20
	v_ashrrev_i32_e32 v23, 31, v22
	v_lshl_add_u64 v[16:17], v[16:17], 2, s[10:11]
	v_lshl_add_u64 v[18:19], v[18:19], 2, s[10:11]
	v_lshl_add_u64 v[20:21], v[20:21], 2, s[10:11]
	v_lshl_add_u64 v[22:23], v[22:23], 2, s[10:11]
	global_load_dword v8, v[8:9], off
	s_nop 0
	global_load_dword v10, v[10:11], off
	s_nop 0
	global_load_dword v9, v[12:13], off
	global_load_dword v11, v[14:15], off
	s_nop 0
	global_load_dword v12, v[16:17], off
	global_load_dword v14, v[18:19], off
	global_load_dword v13, v[20:21], off
	global_load_dword v15, v[22:23], off
	s_and_b32 s65, s77, 0x7f
	s_ashr_i32 s63, s62, 31
	s_mov_b64 s[10:11], s[80:81]
	s_cmp_eq_u32 s65, 0
	s_cbranch_scc1 .LBB0_664
	s_load_dwordx2 s[10:11], s[10:11], 0x110
	s_and_b32 s12, s77, 0xffffff80
	s_ashr_i32 s13, s12, 31
	s_lshl_b64 s[12:13], s[12:13], 14
	v_lshlrev_b32_e32 v100, 3, v98
	s_waitcnt lgkmcnt(0)
	s_add_u32 s3, s10, s12
	s_addc_u32 s12, s11, s13
	s_lshl_b64 s[10:11], s[62:63], 9
	s_add_u32 s10, s3, s10
	s_addc_u32 s11, s12, s11
	s_and_b32 s3, s76, 0x7f
	v_lshl_add_u64 v[16:17], s[10:11], 0, v[100:101]
	v_mov_b32_e32 v114, 0
	v_lshl_add_u64 v[16:17], v[16:17], 0, s[56:57]
	v_mov_b32_e32 v115, v114
	v_mov_b32_e32 v110, v114
	v_mov_b32_e32 v111, v114
	v_mov_b32_e32 v112, v114
	v_mov_b32_e32 v113, v114
	v_mov_b32_e32 v108, v114
	v_mov_b32_e32 v109, v114
	s_add_i32 s10, s3, 7
	s_lshr_b32 s69, s10, 3
	s_lshl_b32 s10, s69, 3
	s_sub_i32 s73, s3, s10
	s_add_i32 s69, s69, -1
	s_mov_b32 s11, 0
	s_add_i32 s12, s73, 0
	s_max_i32 s12, s12, 0
	s_lshl_b32 s10, s12, 14
	v_lshl_add_u64 v[84:85], v[16:17], 0, s[10:11]
	global_load_dwordx2 v[20:21], v[84:85], off
	global_load_dwordx2 v[22:23], v[84:85], off offset:512
	global_load_dwordx2 v[24:25], v[84:85], off offset:1024
	global_load_dwordx2 v[26:27], v[84:85], off offset:1536
	s_add_i32 s12, s73, 1
	s_max_i32 s12, s12, 0
	s_lshl_b32 s10, s12, 14
	v_lshl_add_u64 v[84:85], v[16:17], 0, s[10:11]
	global_load_dwordx2 v[28:29], v[84:85], off
	global_load_dwordx2 v[30:31], v[84:85], off offset:512
	global_load_dwordx2 v[32:33], v[84:85], off offset:1024
	global_load_dwordx2 v[34:35], v[84:85], off offset:1536
	s_add_i32 s12, s73, 2
	s_max_i32 s12, s12, 0
	s_lshl_b32 s10, s12, 14
	v_lshl_add_u64 v[84:85], v[16:17], 0, s[10:11]
	global_load_dwordx2 v[36:37], v[84:85], off
	global_load_dwordx2 v[38:39], v[84:85], off offset:512
	global_load_dwordx2 v[40:41], v[84:85], off offset:1024
; template <bool PASS2>
; __device__ __forceinline__ void s5_tile(const Ctx& C, int T, int sb_lo, int sb_hi, LAS unsigned char* lds, int wave, int lane) {
;     ...
;         const int nb = (k + 15) >> 4, j0 = k - 16 * nb;
;         for (int jb = 0; jb < nb; ++jb) {
; #pragma unroll
;             for (int u = 0; u < 16; ++u) {
;                 const int j = j0 + 16 * jb + u; const bool ok = j >= 0; const int jc = ok ? j : 0;
; #pragma unroll
;                 for (int gi = 0; gi < 4; ++gi) { v2f e = Ep[(size_t)jc * NG * NP + gi * NP]; if (!ok) e = (v2f){0.f, 0.f};
;                     const float nr = fmaf(l8r[gi], sr[gi], fmaf(-l8i[gi], si[gi], e.x)), ni = fmaf(l8r[gi], si[gi], fmaf(l8i[gi], sr[gi], e.y)); sr[gi] = nr; si[gi] = ni; }
;             }
	global_load_dwordx2 v[42:43], v[84:85], off offset:1536
	s_add_i32 s12, s73, 3
	s_max_i32 s12, s12, 0
	s_lshl_b32 s10, s12, 14
	v_lshl_add_u64 v[84:85], v[16:17], 0, s[10:11]
	global_load_dwordx2 v[44:45], v[84:85], off
	global_load_dwordx2 v[46:47], v[84:85], off offset:512
	global_load_dwordx2 v[48:49], v[84:85], off offset:1024
	global_load_dwordx2 v[50:51], v[84:85], off offset:1536
	s_add_i32 s12, s73, 4
	s_max_i32 s12, s12, 0
	s_lshl_b32 s10, s12, 14
	v_lshl_add_u64 v[84:85], v[16:17], 0, s[10:11]
	global_load_dwordx2 v[52:53], v[84:85], off
	global_load_dwordx2 v[54:55], v[84:85], off offset:512
	global_load_dwordx2 v[56:57], v[84:85], off offset:1024
	global_load_dwordx2 v[58:59], v[84:85], off offset:1536
	s_add_i32 s12, s73, 5
	s_max_i32 s12, s12, 0
	s_lshl_b32 s10, s12, 14
	v_lshl_add_u64 v[84:85], v[16:17], 0, s[10:11]
	global_load_dwordx2 v[60:61], v[84:85], off
	global_load_dwordx2 v[62:63], v[84:85], off offset:512
	global_load_dwordx2 v[64:65], v[84:85], off offset:1024
	global_load_dwordx2 v[66:67], v[84:85], off offset:1536
	s_add_i32 s12, s73, 6
	s_max_i32 s12, s12, 0
	s_lshl_b32 s10, s12, 14
	v_lshl_add_u64 v[84:85], v[16:17], 0, s[10:11]
	global_load_dwordx2 v[68:69], v[84:85], off
	global_load_dwordx2 v[70:71], v[84:85], off offset:512
	global_load_dwordx2 v[72:73], v[84:85], off offset:1024
	global_load_dwordx2 v[74:75], v[84:85], off offset:1536
	s_add_i32 s12, s73, 7
	s_max_i32 s12, s12, 0
	s_lshl_b32 s10, s12, 14
	v_lshl_add_u64 v[84:85], v[16:17], 0, s[10:11]
	global_load_dwordx2 v[76:77], v[84:85], off
	global_load_dwordx2 v[78:79], v[84:85], off offset:512
	global_load_dwordx2 v[80:81], v[84:85], off offset:1024
	global_load_dwordx2 v[82:83], v[84:85], off offset:1536
	s_cmp_eq_u32 s69, 0
	s_cbranch_scc1 .Lmy_h_last
.Lmy_h_loop:
	s_waitcnt vmcnt(28)
	s_add_i32 s12, s73, 0
	s_cmp_lt_i32 s12, 0
	s_cbranch_scc1 .Lmy_h_skipA0
	v_fma_f32 v20, -v10, v112, v20
	v_fma_f32 v21, v10, v114, v21
	v_fma_f32 v22, -v11, v113, v22
	v_fma_f32 v23, v11, v115, v23
	v_fma_f32 v24, -v14, v108, v24
	v_fma_f32 v25, v14, v110, v25
	v_fma_f32 v26, -v15, v109, v26
	v_fma_f32 v27, v15, v111, v27
	v_fma_f32 v114, v8, v114, v20
	v_fma_f32 v112, v8, v112, v21
	v_fma_f32 v115, v9, v115, v22
	v_fma_f32 v113, v9, v113, v23
	v_fma_f32 v110, v12, v110, v24
	v_fma_f32 v108, v12, v108, v25
	v_fma_f32 v111, v13, v111, v26
	v_fma_f32 v109, v13, v109, v27
.Lmy_h_skipA0:
	s_add_i32 s12, s12, 8
	s_lshl_b32 s10, s12, 14
	v_lshl_add_u64 v[84:85], v[16:17], 0, s[10:11]
	global_load_dwordx2 v[20:21], v[84:85], off
	global_load_dwordx2 v[22:23], v[84:85], off offset:512
	global_load_dwordx2 v[24:25], v[84:85], off offset:1024
	global_load_dwordx2 v[26:27], v[84:85], off offset:1536
	s_waitcnt vmcnt(28)
	s_add_i32 s12, s73, 1
	s_cmp_lt_i32 s12, 0
	s_cbranch_scc1 .Lmy_h_skipA1
	v_fma_f32 v28, -v10, v112, v28
	v_fma_f32 v29, v10, v114, v29
	v_fma_f32 v30, -v11, v113, v30
	v_fma_f32 v31, v11, v115, v31
	v_fma_f32 v32, -v14, v108, v32
	v_fma_f32 v33, v14, v110, v33
	v_fma_f32 v34, -v15, v109, v34
	v_fma_f32 v35, v15, v111, v35
	v_fma_f32 v114, v8, v114, v28
	v_fma_f32 v112, v8, v112, v29
	v_fma_f32 v115, v9, v115, v30
	v_fma_f32 v113, v9, v113, v31
	v_fma_f32 v110, v12, v110, v32
	v_fma_f32 v108, v12, v108, v33
	v_fma_f32 v111, v13, v111, v34
	v_fma_f32 v109, v13, v109, v35
.Lmy_h_skipA1:
	s_add_i32 s12, s12, 8
	s_lshl_b32 s10, s12, 14
	v_lshl_add_u64 v[84:85], v[16:17], 0, s[10:11]
	global_load_dwordx2 v[28:29], v[84:85], off
	global_load_dwordx2 v[30:31], v[84:85], off offset:512
	global_load_dwordx2 v[32:33], v[84:85], off offset:1024
	global_load_dwordx2 v[34:35], v[84:85], off offset:1536
	s_waitcnt vmcnt(28)
	s_add_i32 s12, s73, 2
	s_cmp_lt_i32 s12, 0
	s_cbranch_scc1 .Lmy_h_skipA2
	v_fma_f32 v36, -v10, v112, v36
	v_fma_f32 v37, v10, v114, v37
	v_fma_f32 v38, -v11, v113, v38
	v_fma_f32 v39, v11, v115, v39
	v_fma_f32 v40, -v14, v108, v40
	v_fma_f32 v41, v14, v110, v41
	v_fma_f32 v42, -v15, v109, v42
	v_fma_f32 v43, v15, v111, v43
	v_fma_f32 v114, v8, v114, v36
	v_fma_f32 v112, v8, v112, v37
	v_fma_f32 v115, v9, v115, v38
	v_fma_f32 v113, v9, v113, v39
	v_fma_f32 v110, v12, v110, v40
	v_fma_f32 v108, v12, v108, v41
	v_fma_f32 v111, v13, v111, v42
	v_fma_f32 v109, v13, v109, v43
; template <bool PASS2>
; __device__ __forceinline__ void s5_tile(const Ctx& C, int T, int sb_lo, int sb_hi, LAS unsigned char* lds, int wave, int lane) {
;     ...
;         for (int jb = 0; jb < nb; ++jb) {
; #pragma unroll
;             for (int u = 0; u < 16; ++u) {
;                 const int j = j0 + 16 * jb + u; const bool ok = j >= 0; const int jc = ok ? j : 0;
; #pragma unroll
;                 for (int gi = 0; gi < 4; ++gi) { v2f e = Ep[(size_t)jc * NG * NP + gi * NP]; if (!ok) e = (v2f){0.f, 0.f};
;                     const float nr = fmaf(l8r[gi], sr[gi], fmaf(-l8i[gi], si[gi], e.x)), ni = fmaf(l8r[gi], si[gi], fmaf(l8i[gi], sr[gi], e.y)); sr[gi] = nr; si[gi] = ni; }
;             }
.Lmy_h_skipA2:
	s_add_i32 s12, s12, 8
	s_lshl_b32 s10, s12, 14
	v_lshl_add_u64 v[84:85], v[16:17], 0, s[10:11]
	global_load_dwordx2 v[36:37], v[84:85], off
	global_load_dwordx2 v[38:39], v[84:85], off offset:512
	global_load_dwordx2 v[40:41], v[84:85], off offset:1024
	global_load_dwordx2 v[42:43], v[84:85], off offset:1536
	s_waitcnt vmcnt(28)
	s_add_i32 s12, s73, 3
	s_cmp_lt_i32 s12, 0
	s_cbranch_scc1 .Lmy_h_skipA3
	v_fma_f32 v44, -v10, v112, v44
	v_fma_f32 v45, v10, v114, v45
	v_fma_f32 v46, -v11, v113, v46
	v_fma_f32 v47, v11, v115, v47
	v_fma_f32 v48, -v14, v108, v48
	v_fma_f32 v49, v14, v110, v49
	v_fma_f32 v50, -v15, v109, v50
	v_fma_f32 v51, v15, v111, v51
	v_fma_f32 v114, v8, v114, v44
	v_fma_f32 v112, v8, v112, v45
	v_fma_f32 v115, v9, v115, v46
	v_fma_f32 v113, v9, v113, v47
	v_fma_f32 v110, v12, v110, v48
	v_fma_f32 v108, v12, v108, v49
	v_fma_f32 v111, v13, v111, v50
	v_fma_f32 v109, v13, v109, v51
.Lmy_h_skipA3:
	s_add_i32 s12, s12, 8
	s_lshl_b32 s10, s12, 14
	v_lshl_add_u64 v[84:85], v[16:17], 0, s[10:11]
	global_load_dwordx2 v[44:45], v[84:85], off
	global_load_dwordx2 v[46:47], v[84:85], off offset:512
	global_load_dwordx2 v[48:49], v[84:85], off offset:1024
	global_load_dwordx2 v[50:51], v[84:85], off offset:1536
	s_waitcnt vmcnt(28)
	s_add_i32 s12, s73, 4
	s_cmp_lt_i32 s12, 0
	s_cbranch_scc1 .Lmy_h_skipA4
	v_fma_f32 v52, -v10, v112, v52
	v_fma_f32 v53, v10, v114, v53
	v_fma_f32 v54, -v11, v113, v54
	v_fma_f32 v55, v11, v115, v55
	v_fma_f32 v56, -v14, v108, v56
	v_fma_f32 v57, v14, v110, v57
	v_fma_f32 v58, -v15, v109, v58
	v_fma_f32 v59, v15, v111, v59
	v_fma_f32 v114, v8, v114, v52
	v_fma_f32 v112, v8, v112, v53
	v_fma_f32 v115, v9, v115, v54
	v_fma_f32 v113, v9, v113, v55
	v_fma_f32 v110, v12, v110, v56
	v_fma_f32 v108, v12, v108, v57
	v_fma_f32 v111, v13, v111, v58
	v_fma_f32 v109, v13, v109, v59
.Lmy_h_skipA4:
	s_add_i32 s12, s12, 8
	s_lshl_b32 s10, s12, 14
	v_lshl_add_u64 v[84:85], v[16:17], 0, s[10:11]
	global_load_dwordx2 v[52:53], v[84:85], off
	global_load_dwordx2 v[54:55], v[84:85], off offset:512
	global_load_dwordx2 v[56:57], v[84:85], off offset:1024
	global_load_dwordx2 v[58:59], v[84:85], off offset:1536
	s_waitcnt vmcnt(28)
	s_add_i32 s12, s73, 5
	s_cmp_lt_i32 s12, 0
	s_cbranch_scc1 .Lmy_h_skipA5
	v_fma_f32 v60, -v10, v112, v60
	v_fma_f32 v61, v10, v114, v61
	v_fma_f32 v62, -v11, v113, v62
	v_fma_f32 v63, v11, v115, v63
	v_fma_f32 v64, -v14, v108, v64
	v_fma_f32 v65, v14, v110, v65
	v_fma_f32 v66, -v15, v109, v66
	v_fma_f32 v67, v15, v111, v67
	v_fma_f32 v114, v8, v114, v60
	v_fma_f32 v112, v8, v112, v61
	v_fma_f32 v115, v9, v115, v62
	v_fma_f32 v113, v9, v113, v63
	v_fma_f32 v110, v12, v110, v64
	v_fma_f32 v108, v12, v108, v65
	v_fma_f32 v111, v13, v111, v66
	v_fma_f32 v109, v13, v109, v67
.Lmy_h_skipA5:
	s_add_i32 s12, s12, 8
	s_lshl_b32 s10, s12, 14
	v_lshl_add_u64 v[84:85], v[16:17], 0, s[10:11]
	global_load_dwordx2 v[60:61], v[84:85], off
	global_load_dwordx2 v[62:63], v[84:85], off offset:512
	global_load_dwordx2 v[64:65], v[84:85], off offset:1024
	global_load_dwordx2 v[66:67], v[84:85], off offset:1536
	s_waitcnt vmcnt(28)
	s_add_i32 s12, s73, 6
	s_cmp_lt_i32 s12, 0
	s_cbranch_scc1 .Lmy_h_skipA6
	v_fma_f32 v68, -v10, v112, v68
	v_fma_f32 v69, v10, v114, v69
	v_fma_f32 v70, -v11, v113, v70
	v_fma_f32 v71, v11, v115, v71
	v_fma_f32 v72, -v14, v108, v72
	v_fma_f32 v73, v14, v110, v73
	v_fma_f32 v74, -v15, v109, v74
	v_fma_f32 v75, v15, v111, v75
	v_fma_f32 v114, v8, v114, v68
	v_fma_f32 v112, v8, v112, v69
	v_fma_f32 v115, v9, v115, v70
	v_fma_f32 v113, v9, v113, v71
	v_fma_f32 v110, v12, v110, v72
	v_fma_f32 v108, v12, v108, v73
	v_fma_f32 v111, v13, v111, v74
	v_fma_f32 v109, v13, v109, v75
.Lmy_h_skipA6:
	s_add_i32 s12, s12, 8
	s_lshl_b32 s10, s12, 14
	v_lshl_add_u64 v[84:85], v[16:17], 0, s[10:11]
	global_load_dwordx2 v[68:69], v[84:85], off
	global_load_dwordx2 v[70:71], v[84:85], off offset:512
	global_load_dwordx2 v[72:73], v[84:85], off offset:1024
	global_load_dwordx2 v[74:75], v[84:85], off offset:1536
	s_waitcnt vmcnt(28)
	s_add_i32 s12, s73, 7
	s_cmp_lt_i32 s12, 0
	s_cbranch_scc1 .Lmy_h_skipA7
	v_fma_f32 v76, -v10, v112, v76
	v_fma_f32 v77, v10, v114, v77
	v_fma_f32 v78, -v11, v113, v78
	v_fma_f32 v79, v11, v115, v79
	v_fma_f32 v80, -v14, v108, v80
	v_fma_f32 v81, v14, v110, v81
	v_fma_f32 v82, -v15, v109, v82
	v_fma_f32 v83, v15, v111, v83
	v_fma_f32 v114, v8, v114, v76
	v_fma_f32 v112, v8, v112, v77
	v_fma_f32 v115, v9, v115, v78
	v_fma_f32 v113, v9, v113, v79
	v_fma_f32 v110, v12, v110, v80
	v_fma_f32 v108, v12, v108, v81
	v_fma_f32 v111, v13, v111, v82
	v_fma_f32 v109, v13, v109, v83
.Lmy_h_skipA7:
	s_add_i32 s12, s12, 8
	s_lshl_b32 s10, s12, 14
	v_lshl_add_u64 v[84:85], v[16:17], 0, s[10:11]
	global_load_dwordx2 v[76:77], v[84:85], off
	global_load_dwordx2 v[78:79], v[84:85], off offset:512
	global_load_dwordx2 v[80:81], v[84:85], off offset:1024
	global_load_dwordx2 v[82:83], v[84:85], off offset:1536
	s_add_i32 s73, s73, 8
	s_add_i32 s69, s69, -1
	s_cmp_lg_u32 s69, 0
	s_cbranch_scc1 .Lmy_h_loop

; template <bool PASS2>
; __device__ __forceinline__ void s5_tile(const Ctx& C, int T, int sb_lo, int sb_hi, LAS unsigned char* lds, int wave, int lane) {
;     ...
;         for (int jb = 0; jb < nb; ++jb) {
; #pragma unroll
;             for (int u = 0; u < 16; ++u) {
;                 const int j = j0 + 16 * jb + u; const bool ok = j >= 0; const int jc = ok ? j : 0;
; #pragma unroll
;                 for (int gi = 0; gi < 4; ++gi) { v2f e = Ep[(size_t)jc * NG * NP + gi * NP]; if (!ok) e = (v2f){0.f, 0.f};
;                     const float nr = fmaf(l8r[gi], sr[gi], fmaf(-l8i[gi], si[gi], e.x)), ni = fmaf(l8r[gi], si[gi], fmaf(l8i[gi], sr[gi], e.y)); sr[gi] = nr; si[gi] = ni; }
;             }
;         }
.Lmy_h_skipB0:
	s_waitcnt vmcnt(24)
	s_add_i32 s12, s73, 1
	s_cmp_lt_i32 s12, 0
	s_cbranch_scc1 .Lmy_h_skipB1
	v_fma_f32 v28, -v10, v112, v28
	v_fma_f32 v29, v10, v114, v29
	v_fma_f32 v30, -v11, v113, v30
	v_fma_f32 v31, v11, v115, v31
	v_fma_f32 v32, -v14, v108, v32
	v_fma_f32 v33, v14, v110, v33
	v_fma_f32 v34, -v15, v109, v34
	v_fma_f32 v35, v15, v111, v35
	v_fma_f32 v114, v8, v114, v28
	v_fma_f32 v112, v8, v112, v29
	v_fma_f32 v115, v9, v115, v30
	v_fma_f32 v113, v9, v113, v31
	v_fma_f32 v110, v12, v110, v32
	v_fma_f32 v108, v12, v108, v33
	v_fma_f32 v111, v13, v111, v34
	v_fma_f32 v109, v13, v109, v35
.Lmy_h_skipB1:
	s_waitcnt vmcnt(20)
	s_add_i32 s12, s73, 2
	s_cmp_lt_i32 s12, 0
	s_cbranch_scc1 .Lmy_h_skipB2
	v_fma_f32 v36, -v10, v112, v36
	v_fma_f32 v37, v10, v114, v37
	v_fma_f32 v38, -v11, v113, v38
	v_fma_f32 v39, v11, v115, v39
	v_fma_f32 v40, -v14, v108, v40
	v_fma_f32 v41, v14, v110, v41
	v_fma_f32 v42, -v15, v109, v42
	v_fma_f32 v43, v15, v111, v43
	v_fma_f32 v114, v8, v114, v36
	v_fma_f32 v112, v8, v112, v37
	v_fma_f32 v115, v9, v115, v38
	v_fma_f32 v113, v9, v113, v39
	v_fma_f32 v110, v12, v110, v40
	v_fma_f32 v108, v12, v108, v41
	v_fma_f32 v111, v13, v111, v42
	v_fma_f32 v109, v13, v109, v43
.Lmy_h_skipB2:
	s_waitcnt vmcnt(16)
	s_add_i32 s12, s73, 3
	s_cmp_lt_i32 s12, 0
	s_cbranch_scc1 .Lmy_h_skipB3
	v_fma_f32 v44, -v10, v112, v44
	v_fma_f32 v45, v10, v114, v45
	v_fma_f32 v46, -v11, v113, v46
	v_fma_f32 v47, v11, v115, v47
	v_fma_f32 v48, -v14, v108, v48
	v_fma_f32 v49, v14, v110, v49
	v_fma_f32 v50, -v15, v109, v50
	v_fma_f32 v51, v15, v111, v51
	v_fma_f32 v114, v8, v114, v44
	v_fma_f32 v112, v8, v112, v45
	v_fma_f32 v115, v9, v115, v46
	v_fma_f32 v113, v9, v113, v47
	v_fma_f32 v110, v12, v110, v48
	v_fma_f32 v108, v12, v108, v49
	v_fma_f32 v111, v13, v111, v50
	v_fma_f32 v109, v13, v109, v51
.Lmy_h_skipB3:
	s_waitcnt vmcnt(12)
	s_add_i32 s12, s73, 4
	s_cmp_lt_i32 s12, 0
	s_cbranch_scc1 .Lmy_h_skipB4
	v_fma_f32 v52, -v10, v112, v52
	v_fma_f32 v53, v10, v114, v53
	v_fma_f32 v54, -v11, v113, v54
	v_fma_f32 v55, v11, v115, v55
	v_fma_f32 v56, -v14, v108, v56
	v_fma_f32 v57, v14, v110, v57
	v_fma_f32 v58, -v15, v109, v58
	v_fma_f32 v59, v15, v111, v59
	v_fma_f32 v114, v8, v114, v52
	v_fma_f32 v112, v8, v112, v53
	v_fma_f32 v115, v9, v115, v54
	v_fma_f32 v113, v9, v113, v55
	v_fma_f32 v110, v12, v110, v56
	v_fma_f32 v108, v12, v108, v57
	v_fma_f32 v111, v13, v111, v58
	v_fma_f32 v109, v13, v109, v59
.Lmy_h_skipB4:
	s_waitcnt vmcnt(8)
	s_add_i32 s12, s73, 5
	s_cmp_lt_i32 s12, 0
	s_cbranch_scc1 .Lmy_h_skipB5
	v_fma_f32 v60, -v10, v112, v60
	v_fma_f32 v61, v10, v114, v61
	v_fma_f32 v62, -v11, v113, v62
	v_fma_f32 v63, v11, v115, v63
	v_fma_f32 v64, -v14, v108, v64
	v_fma_f32 v65, v14, v110, v65
	v_fma_f32 v66, -v15, v109, v66
	v_fma_f32 v67, v15, v111, v67
	v_fma_f32 v114, v8, v114, v60
	v_fma_f32 v112, v8, v112, v61
	v_fma_f32 v115, v9, v115, v62
	v_fma_f32 v113, v9, v113, v63
	v_fma_f32 v110, v12, v110, v64
	v_fma_f32 v108, v12, v108, v65
	v_fma_f32 v111, v13, v111, v66
	v_fma_f32 v109, v13, v109, v67
.Lmy_h_skipB5:
	s_waitcnt vmcnt(4)
	s_add_i32 s12, s73, 6
	s_cmp_lt_i32 s12, 0
	s_cbranch_scc1 .Lmy_h_skipB6
	v_fma_f32 v68, -v10, v112, v68
	v_fma_f32 v69, v10, v114, v69
	v_fma_f32 v70, -v11, v113, v70
	v_fma_f32 v71, v11, v115, v71
	v_fma_f32 v72, -v14, v108, v72
	v_fma_f32 v73, v14, v110, v73
	v_fma_f32 v74, -v15, v109, v74
	v_fma_f32 v75, v15, v111, v75
	v_fma_f32 v114, v8, v114, v68
	v_fma_f32 v112, v8, v112, v69
	v_fma_f32 v115, v9, v115, v70
	v_fma_f32 v113, v9, v113, v71
	v_fma_f32 v110, v12, v110, v72
	v_fma_f32 v108, v12, v108, v73
	v_fma_f32 v111, v13, v111, v74
	v_fma_f32 v109, v13, v109, v75
.Lmy_h_skipB6:
	s_waitcnt vmcnt(0)
	s_add_i32 s12, s73, 7
	s_cmp_lt_i32 s12, 0
	s_cbranch_scc1 .Lmy_h_skipB7
	v_fma_f32 v76, -v10, v112, v76
	v_fma_f32 v77, v10, v114, v77
	v_fma_f32 v78, -v11, v113, v78
	v_fma_f32 v79, v11, v115, v79
	v_fma_f32 v80, -v14, v108, v80
	v_fma_f32 v81, v14, v110, v81
	v_fma_f32 v82, -v15, v109, v82
	v_fma_f32 v83, v15, v111, v83
	v_fma_f32 v114, v8, v114, v76
	v_fma_f32 v112, v8, v112, v77
	v_fma_f32 v115, v9, v115, v78
	v_fma_f32 v113, v9, v113, v79
	v_fma_f32 v110, v12, v110, v80
	v_fma_f32 v108, v12, v108, v81
	v_fma_f32 v111, v13, v111, v82
	v_fma_f32 v109, v13, v109, v83
.Lmy_h_skipB7:
	v_readlane_b32 s70, v232, 6
	s_branch .LBB0_665
